# v30 + strategy 7.2 cleanup: 63 lgkmcnt waits that provably guard nothing (straight-line count analysis; mostly left behind the ds_bpermute->DPP change in the MLA epilogue) deleted
# speedup vs baseline: 1.0042x; 1.0011x over previous
.LBB0_395:
	s_cmp_lg_u32 0, -1
	s_cselect_b32 s2, 0, 0
	s_add_i32 s2, s2, 0x14000
	v_add_u32_e32 v56, s2, v193
	ds_read_b64_tr_b16 v[4:5], v56 offset:0
	ds_read_b64_tr_b16 v[6:7], v56 offset:0x800
	ds_read_b64_tr_b16 v[8:9], v56 offset:0x1000
	v_pk_mul_f32 v[32:33], v[32:33], v[2:3] op_sel_hi:[1,0]
	v_pk_mul_f32 v[30:31], v[30:31], v[2:3] op_sel_hi:[1,0]
	v_pk_mul_f32 v[28:29], v[28:29], v[2:3] op_sel_hi:[1,0]
	v_pk_mul_f32 v[26:27], v[26:27], v[2:3] op_sel_hi:[1,0]
	v_pk_mul_f32 v[24:25], v[24:25], v[2:3] op_sel_hi:[1,0]
	v_pk_mul_f32 v[22:23], v[22:23], v[2:3] op_sel_hi:[1,0]
	v_pk_mul_f32 v[20:21], v[20:21], v[2:3] op_sel_hi:[1,0]
	v_pk_mul_f32 v[18:19], v[18:19], v[2:3] op_sel_hi:[1,0]
	ds_read_b64_tr_b16 v[10:11], v56 offset:0x1800
	v_lshlrev_b32_e32 v2, 2, v186
	v_and_b32_e32 v55, 16, v186
	ds_read_b64_tr_b16 v[12:13], v56 offset:0x2000
	v_and_b32_e32 v2, 12, v2
	v_bfe_u32 v54, v186, 2, 2
	ds_read_b64_tr_b16 v[14:15], v56 offset:0x2800
	v_or3_b32 v2, v55, v2, s33
	v_lshlrev_b32_e32 v103, 3, v188
	ds_read_b64_tr_b16 v[50:51], v56 offset:0x3000
	v_or_b32_e32 v55, v103, v54
	v_lshlrev_b32_e32 v2, 1, v2
	v_lshlrev_b32_e32 v54, 4, v54
	ds_read_b64_tr_b16 v[52:53], v56 offset:0x3800
	v_lshlrev_b32_e32 v56, 8, v55
	v_bitop3_b32 v54, v2, v54, s56 bitop3:0x6c
	v_add3_u32 v104, v56, s46, v54
	v_or_b32_e32 v54, 4, v55
	v_lshlrev_b32_e32 v55, 8, v54
	v_lshlrev_b32_e32 v54, 4, v54
	v_and_b32_e32 v54, 0x70, v54
	v_bitop3_b32 v2, v2, v54, s56 bitop3:0x6c
	v_add3_u32 v2, v55, s46, v2
	ds_read_b64_tr_b16 v[54:55], v104 offset:0
	ds_read_b64_tr_b16 v[56:57], v2 offset:0
	ds_read_b64_tr_b16 v[58:59], v104 offset:0x1000
	ds_read_b64_tr_b16 v[60:61], v2 offset:0x1000
	ds_read_b64_tr_b16 v[62:63], v104 offset:0x2000
	ds_read_b64_tr_b16 v[64:65], v2 offset:0x2000
	ds_read_b64_tr_b16 v[192:193], v104 offset:0x3000
	ds_read_b64_tr_b16 v[194:195], v2 offset:0x3000
	s_waitcnt lgkmcnt(0)
	s_nop 0
	v_mfma_f32_32x32x16_bf16 v[18:33], v[54:57], v[4:7], v[18:33]
	s_add_i32 s2, 0, 0x18000
	v_add_u32_e32 v7, s47, v103
	v_mov_b32_e32 v2, 1.0
	v_add_u32_e32 v6, s2, v190
	v_add_u32_e32 v4, 16, v7
	s_barrier
	v_mfma_f32_32x32x16_bf16 v[18:33], v[58:61], v[8:11], v[18:33]
	v_xad_u32 v10, v4, v189, v6
	v_xad_u32 v8, v7, v189, v6
	v_add_u32_e32 v9, 32, v7
	s_andn2_b64 vcc, exec, s[28:29]
	v_mfma_f32_32x32x16_bf16 v[18:33], v[62:65], v[12:15], v[18:33]
	v_mfma_f32_32x32x16_bf16 v[18:33], v[192:195], v[50:53], v[18:33]
	s_nop 11
	v_mul_f32_e32 v4, v18, v2
	v_mul_f32_e32 v5, v19, v2
	v_mul_f32_e32 v11, v20, v2
	v_mul_f32_e32 v12, v21, v2
	v_cvt_pk_bf16_f32 v4, v4, v5
	v_cvt_pk_bf16_f32 v5, v11, v12
	v_mul_f32_e32 v13, v22, v2
	v_mul_f32_e32 v14, v23, v2
	v_mul_f32_e32 v15, v24, v2
	v_mul_f32_e32 v50, v25, v2
	ds_write_b64 v8, v[4:5]
	v_cvt_pk_bf16_f32 v4, v13, v14
	v_cvt_pk_bf16_f32 v5, v15, v50
	v_mul_f32_e32 v51, v26, v2
	v_mul_f32_e32 v52, v27, v2
	v_mul_f32_e32 v53, v28, v2
	v_mul_f32_e32 v54, v29, v2
	ds_write_b64 v10, v[4:5]
	v_cvt_pk_bf16_f32 v4, v51, v52
	v_cvt_pk_bf16_f32 v5, v53, v54
	v_xad_u32 v8, v9, v189, v6
	ds_write_b64 v8, v[4:5]
	v_mul_f32_e32 v4, v30, v2
	v_mul_f32_e32 v5, v31, v2
	v_cvt_pk_bf16_f32 v4, v4, v5
	v_mul_f32_e32 v5, v32, v2
	v_mul_f32_e32 v2, v33, v2
	v_cvt_pk_bf16_f32 v5, v5, v2
	v_add_u32_e32 v2, 48, v7
	v_xad_u32 v2, v2, v189, v6
	ds_write_b64 v2, v[4:5]
	s_cbranch_vccnz .LBB0_431
	v_lshl_add_u32 v2, v186, 2, s48
	ds_read_b32 v204, v2
	ds_read_b32 v205, v2 offset:256
	ds_read_b32 v206, v2 offset:512
	ds_read_b32 v207, v2 offset:768
	ds_read_b32 v208, v2 offset:1024
	ds_read_b32 v209, v2 offset:1280
	ds_read_b32 v210, v2 offset:1536
	ds_read_b32 v211, v2 offset:1792
	ds_read_b32 v212, v2 offset:2048
	ds_read_b32 v213, v2 offset:2304
	ds_read_b32 v214, v2 offset:2560
	ds_read_b32 v215, v2 offset:2816
	ds_read_b32 v216, v2 offset:3072
	ds_read_b32 v217, v2 offset:3328
	ds_read_b32 v218, v2 offset:3584
	ds_read_b32 v219, v2 offset:3840
	s_add_i32 s10, s58, s22
	s_ashr_i32 s11, s10, 31
	s_lshl_b64 s[10:11], s[10:11], 13
	s_add_u32 s42, s59, s10
	v_lshl_or_b32 v4, v188, 14, v187
	v_and_b32_e32 v5, 1, v186
	s_addc_u32 s43, s60, s11
	v_cmp_eq_u32_e64 s[10:11], 0, v5
	v_ashrrev_i32_e32 v5, 31, v4
	s_waitcnt lgkmcnt(0)
	v_add_f32_e32 v6, v34, v204
	v_lshl_add_u64 v[4:5], v[4:5], 1, s[42:43]
	s_nop 0
	v_mov_b32_dpp v7, v6 quad_perm:[1,0,3,2] row_mask:0xf bank_mask:0xf bound_ctrl:1
	s_and_saveexec_b64 s[42:43], s[10:11]
	s_cbranch_execz .LBB0_398
	v_cvt_pk_bf16_f32 v6, v6, v7
	global_store_dword v[4:5], v6, off

.LBB0_528:
	s_or_b64 exec, exec, s[18:19]
	s_waitcnt lgkmcnt(0)
	v_add_u32_e32 v2, s23, v193
	v_and_b32_e32 v86, 64, v202
	ds_read_b128 v[82:85], v2
	ds_read_b128 v[12:15], v2 offset:32
	ds_read_b128 v[8:11], v2 offset:64
	ds_read_b128 v[4:7], v2 offset:96
	v_xor_b32_e32 v2, 1, v202
	v_add_u32_e32 v86, 64, v86
	s_add_i32 s16, s31, s16
	v_cmp_lt_i32_e32 vcc, v2, v86
	s_ashr_i32 s17, s16, 31
	s_lshl_b64 s[16:17], s[16:17], 13
	v_cndmask_b32_e32 v2, v202, v2, vcc
	v_lshlrev_b32_e32 v86, 2, v2
	s_waitcnt lgkmcnt(3)
	v_mul_f32_e32 v66, v66, v82
	v_lshl_add_u64 v[16:17], v[158:159], 0, s[16:17]
	s_lshl_b32 s12, s30, 8
	s_nop 1
	v_mov_b32_dpp v87, v66 quad_perm:[1,0,3,2] row_mask:0xf bank_mask:0xf bound_ctrl:1
	v_lshl_add_u64 v[16:17], v[16:17], 0, s[12:13]
	v_lshlrev_b32_e32 v2, 1, v160
	s_waitcnt lgkmcnt(0)
	v_lshl_add_u64 v[16:17], v[16:17], 0, v[2:3]
	v_lshl_add_u64 v[16:17], v[16:17], 0, v[176:177]
	v_lshl_add_u64 v[16:17], v[16:17], 0, s[14:15]
	s_and_saveexec_b64 s[16:17], s[8:9]
	s_cbranch_execz .LBB0_530
	v_cvt_pk_bf16_f32 v2, v66, v87
	global_store_dword v[16:17], v2, off

.LBB0_536:
	s_or_b64 exec, exec, s[16:17]
	v_mul_f32_e32 v2, v67, v83
	s_waitcnt lgkmcnt(0)
	s_nop 1
	v_mov_b32_dpp v18, v2 quad_perm:[1,0,3,2] row_mask:0xf bank_mask:0xf bound_ctrl:1
	s_and_saveexec_b64 s[16:17], s[8:9]
	s_cbranch_execz .LBB0_538
	v_add_co_u32_e32 v66, vcc, 0x2000, v16
	v_cvt_pk_bf16_f32 v2, v2, v18
	s_nop 0
	v_addc_co_u32_e32 v67, vcc, 0, v17, vcc
	global_store_dword v[66:67], v2, off
.LBB0_538:
	s_or_b64 exec, exec, s[16:17]
	v_mul_f32_e32 v2, v51, v83
	s_waitcnt lgkmcnt(0)
	s_nop 1
	v_mov_b32_dpp v18, v2 quad_perm:[1,0,3,2] row_mask:0xf bank_mask:0xf bound_ctrl:1
	s_and_saveexec_b64 s[16:17], s[8:9]
	s_cbranch_execz .LBB0_540
	v_add_co_u32_e32 v50, vcc, 0x2000, v16
	v_cvt_pk_bf16_f32 v2, v2, v18
	s_nop 0
	v_addc_co_u32_e32 v51, vcc, 0, v17, vcc
	global_store_dword v[50:51], v2, off offset:64
.LBB0_540:
	s_or_b64 exec, exec, s[16:17]
	v_mul_f32_e32 v2, v35, v83
	s_waitcnt lgkmcnt(0)
	s_nop 1
	v_mov_b32_dpp v18, v2 quad_perm:[1,0,3,2] row_mask:0xf bank_mask:0xf bound_ctrl:1
	s_and_saveexec_b64 s[16:17], s[8:9]
	s_cbranch_execz .LBB0_542
	v_add_co_u32_e32 v34, vcc, 0x2000, v16
	v_cvt_pk_bf16_f32 v2, v2, v18
	s_nop 0
	v_addc_co_u32_e32 v35, vcc, 0, v17, vcc
	global_store_dword v[34:35], v2, off offset:128
.LBB0_542:
	s_or_b64 exec, exec, s[16:17]
	v_mul_f32_e32 v2, v19, v83
	s_waitcnt lgkmcnt(0)
	s_nop 1
	v_mov_b32_dpp v18, v2 quad_perm:[1,0,3,2] row_mask:0xf bank_mask:0xf bound_ctrl:1
	s_and_saveexec_b64 s[16:17], s[8:9]
	s_cbranch_execz .LBB0_544
	v_cvt_pk_bf16_f32 v2, v2, v18
	v_add_co_u32_e32 v18, vcc, 0x2000, v16
	s_nop 1
	v_addc_co_u32_e32 v19, vcc, 0, v17, vcc
	global_store_dword v[18:19], v2, off offset:192
.LBB0_544:
	s_or_b64 exec, exec, s[16:17]
	v_mul_f32_e32 v2, v68, v84
	s_waitcnt lgkmcnt(0)
	s_nop 1
	v_mov_b32_dpp v18, v2 quad_perm:[1,0,3,2] row_mask:0xf bank_mask:0xf bound_ctrl:1
	s_and_saveexec_b64 s[16:17], s[8:9]
	s_cbranch_execz .LBB0_546
	v_cvt_pk_bf16_f32 v2, v2, v18
	v_add_co_u32_e32 v18, vcc, 0x4000, v16
	s_nop 1
	v_addc_co_u32_e32 v19, vcc, 0, v17, vcc
	global_store_dword v[18:19], v2, off
.LBB0_546:
	s_or_b64 exec, exec, s[16:17]
	v_mul_f32_e32 v2, v52, v84
	s_waitcnt lgkmcnt(0)
	s_nop 1
	v_mov_b32_dpp v18, v2 quad_perm:[1,0,3,2] row_mask:0xf bank_mask:0xf bound_ctrl:1
	s_and_saveexec_b64 s[16:17], s[8:9]
	s_cbranch_execz .LBB0_548
	v_cvt_pk_bf16_f32 v2, v2, v18
	v_add_co_u32_e32 v18, vcc, 0x4000, v16
	s_nop 1
	v_addc_co_u32_e32 v19, vcc, 0, v17, vcc
	global_store_dword v[18:19], v2, off offset:64
.LBB0_548:
	s_or_b64 exec, exec, s[16:17]
	v_mul_f32_e32 v2, v36, v84
	s_waitcnt lgkmcnt(0)
	s_nop 1
	v_mov_b32_dpp v18, v2 quad_perm:[1,0,3,2] row_mask:0xf bank_mask:0xf bound_ctrl:1
	s_and_saveexec_b64 s[16:17], s[8:9]
	s_cbranch_execz .LBB0_550
	v_cvt_pk_bf16_f32 v2, v2, v18
	v_add_co_u32_e32 v18, vcc, 0x4000, v16
	s_nop 1
	v_addc_co_u32_e32 v19, vcc, 0, v17, vcc
	global_store_dword v[18:19], v2, off offset:128
.LBB0_550:
	s_or_b64 exec, exec, s[16:17]
	v_mul_f32_e32 v2, v20, v84
	s_waitcnt lgkmcnt(0)
	s_nop 1
	v_mov_b32_dpp v18, v2 quad_perm:[1,0,3,2] row_mask:0xf bank_mask:0xf bound_ctrl:1
	s_and_saveexec_b64 s[16:17], s[8:9]
	s_cbranch_execz .LBB0_552
	v_cvt_pk_bf16_f32 v2, v2, v18
	v_add_co_u32_e32 v18, vcc, 0x4000, v16
	s_nop 1
	v_addc_co_u32_e32 v19, vcc, 0, v17, vcc
	global_store_dword v[18:19], v2, off offset:192
.LBB0_552:
	s_or_b64 exec, exec, s[16:17]
	v_mul_f32_e32 v2, v69, v85
	s_waitcnt lgkmcnt(0)
	s_nop 1
	v_mov_b32_dpp v18, v2 quad_perm:[1,0,3,2] row_mask:0xf bank_mask:0xf bound_ctrl:1
	s_and_saveexec_b64 s[16:17], s[8:9]
	s_cbranch_execz .LBB0_554
	v_cvt_pk_bf16_f32 v2, v2, v18
	v_add_co_u32_e32 v18, vcc, 0x6000, v16
	s_nop 1
	v_addc_co_u32_e32 v19, vcc, 0, v17, vcc
	global_store_dword v[18:19], v2, off
.LBB0_554:
	s_or_b64 exec, exec, s[16:17]
	v_mul_f32_e32 v2, v53, v85
	s_waitcnt lgkmcnt(0)
	s_nop 1
	v_mov_b32_dpp v18, v2 quad_perm:[1,0,3,2] row_mask:0xf bank_mask:0xf bound_ctrl:1
	s_and_saveexec_b64 s[16:17], s[8:9]
	s_cbranch_execz .LBB0_556
	v_cvt_pk_bf16_f32 v2, v2, v18
	v_add_co_u32_e32 v18, vcc, 0x6000, v16
	s_nop 1
	v_addc_co_u32_e32 v19, vcc, 0, v17, vcc
	global_store_dword v[18:19], v2, off offset:64
.LBB0_556:
	s_or_b64 exec, exec, s[16:17]
	v_mul_f32_e32 v2, v37, v85
	s_waitcnt lgkmcnt(0)
	s_nop 1
	v_mov_b32_dpp v18, v2 quad_perm:[1,0,3,2] row_mask:0xf bank_mask:0xf bound_ctrl:1
	s_and_saveexec_b64 s[16:17], s[8:9]
	s_cbranch_execz .LBB0_558
	v_cvt_pk_bf16_f32 v2, v2, v18
	v_add_co_u32_e32 v18, vcc, 0x6000, v16
	s_nop 1
	v_addc_co_u32_e32 v19, vcc, 0, v17, vcc
	global_store_dword v[18:19], v2, off offset:128
.LBB0_558:
	s_or_b64 exec, exec, s[16:17]
	v_mul_f32_e32 v2, v21, v85
	s_waitcnt lgkmcnt(0)
	s_nop 1
	v_mov_b32_dpp v18, v2 quad_perm:[1,0,3,2] row_mask:0xf bank_mask:0xf bound_ctrl:1
	s_and_saveexec_b64 s[16:17], s[8:9]
	s_cbranch_execz .LBB0_560
	v_cvt_pk_bf16_f32 v2, v2, v18
	v_add_co_u32_e32 v18, vcc, 0x6000, v16
	s_nop 1
	v_addc_co_u32_e32 v19, vcc, 0, v17, vcc
	global_store_dword v[18:19], v2, off offset:192
.LBB0_560:
	s_or_b64 exec, exec, s[16:17]
	v_mul_f32_e32 v2, v70, v12
	s_waitcnt lgkmcnt(0)
	s_nop 1
	v_mov_b32_dpp v18, v2 quad_perm:[1,0,3,2] row_mask:0xf bank_mask:0xf bound_ctrl:1
	s_and_saveexec_b64 s[16:17], s[8:9]
	s_cbranch_execz .LBB0_562
	v_cvt_pk_bf16_f32 v2, v2, v18
	v_add_co_u32_e32 v18, vcc, 0x10000, v16
	s_nop 1
	v_addc_co_u32_e32 v19, vcc, 0, v17, vcc
	global_store_dword v[18:19], v2, off
.LBB0_562:
	s_or_b64 exec, exec, s[16:17]
	v_mul_f32_e32 v2, v54, v12
	s_waitcnt lgkmcnt(0)
	s_nop 1
	v_mov_b32_dpp v18, v2 quad_perm:[1,0,3,2] row_mask:0xf bank_mask:0xf bound_ctrl:1
	s_and_saveexec_b64 s[16:17], s[8:9]
	s_cbranch_execz .LBB0_564
	v_cvt_pk_bf16_f32 v2, v2, v18
	v_add_co_u32_e32 v18, vcc, 0x10000, v16
	s_nop 1
	v_addc_co_u32_e32 v19, vcc, 0, v17, vcc
	global_store_dword v[18:19], v2, off offset:64
.LBB0_564:
	s_or_b64 exec, exec, s[16:17]
	v_mul_f32_e32 v2, v38, v12
	s_waitcnt lgkmcnt(0)
	s_nop 1
	v_mov_b32_dpp v18, v2 quad_perm:[1,0,3,2] row_mask:0xf bank_mask:0xf bound_ctrl:1
	s_and_saveexec_b64 s[16:17], s[8:9]
	s_cbranch_execz .LBB0_566
	v_cvt_pk_bf16_f32 v2, v2, v18
	v_add_co_u32_e32 v18, vcc, 0x10000, v16
	s_nop 1
	v_addc_co_u32_e32 v19, vcc, 0, v17, vcc
	global_store_dword v[18:19], v2, off offset:128

.LBB0_568:
	s_or_b64 exec, exec, s[16:17]
	v_mul_f32_e32 v2, v71, v13
	s_waitcnt lgkmcnt(0)
	s_nop 1
	v_mov_b32_dpp v12, v2 quad_perm:[1,0,3,2] row_mask:0xf bank_mask:0xf bound_ctrl:1
	s_and_saveexec_b64 s[16:17], s[8:9]
	s_cbranch_execz .LBB0_570
	v_add_co_u32_e32 v18, vcc, 0x12000, v16
	v_cvt_pk_bf16_f32 v2, v2, v12
	s_nop 0
	v_addc_co_u32_e32 v19, vcc, 0, v17, vcc
	global_store_dword v[18:19], v2, off
.LBB0_570:
	s_or_b64 exec, exec, s[16:17]
	v_mul_f32_e32 v2, v55, v13
	s_waitcnt lgkmcnt(0)
	s_nop 1
	v_mov_b32_dpp v12, v2 quad_perm:[1,0,3,2] row_mask:0xf bank_mask:0xf bound_ctrl:1
	s_and_saveexec_b64 s[16:17], s[8:9]
	s_cbranch_execz .LBB0_572
	v_add_co_u32_e32 v18, vcc, 0x12000, v16
	v_cvt_pk_bf16_f32 v2, v2, v12
	s_nop 0
	v_addc_co_u32_e32 v19, vcc, 0, v17, vcc
	global_store_dword v[18:19], v2, off offset:64
.LBB0_572:
	s_or_b64 exec, exec, s[16:17]
	v_mul_f32_e32 v2, v39, v13
	s_waitcnt lgkmcnt(0)
	s_nop 1
	v_mov_b32_dpp v12, v2 quad_perm:[1,0,3,2] row_mask:0xf bank_mask:0xf bound_ctrl:1
	s_and_saveexec_b64 s[16:17], s[8:9]
	s_cbranch_execz .LBB0_574
	v_add_co_u32_e32 v18, vcc, 0x12000, v16
	v_cvt_pk_bf16_f32 v2, v2, v12
	s_nop 0
	v_addc_co_u32_e32 v19, vcc, 0, v17, vcc
	global_store_dword v[18:19], v2, off offset:128
.LBB0_574:
	s_or_b64 exec, exec, s[16:17]
	v_mul_f32_e32 v2, v23, v13
	s_waitcnt lgkmcnt(0)
	s_nop 1
	v_mov_b32_dpp v12, v2 quad_perm:[1,0,3,2] row_mask:0xf bank_mask:0xf bound_ctrl:1
	s_and_saveexec_b64 s[16:17], s[8:9]
	s_cbranch_execz .LBB0_576
	v_cvt_pk_bf16_f32 v2, v2, v12
	v_add_co_u32_e32 v12, vcc, 0x12000, v16
	s_nop 1
	v_addc_co_u32_e32 v13, vcc, 0, v17, vcc
	global_store_dword v[12:13], v2, off offset:192
.LBB0_576:
	s_or_b64 exec, exec, s[16:17]
	v_mul_f32_e32 v2, v72, v14
	s_waitcnt lgkmcnt(0)
	s_nop 1
	v_mov_b32_dpp v12, v2 quad_perm:[1,0,3,2] row_mask:0xf bank_mask:0xf bound_ctrl:1
	s_and_saveexec_b64 s[16:17], s[8:9]
	s_cbranch_execz .LBB0_578
	v_cvt_pk_bf16_f32 v2, v2, v12
	v_add_co_u32_e32 v12, vcc, 0x14000, v16
	s_nop 1
	v_addc_co_u32_e32 v13, vcc, 0, v17, vcc
	global_store_dword v[12:13], v2, off
.LBB0_578:
	s_or_b64 exec, exec, s[16:17]
	v_mul_f32_e32 v2, v56, v14
	s_waitcnt lgkmcnt(0)
	s_nop 1
	v_mov_b32_dpp v12, v2 quad_perm:[1,0,3,2] row_mask:0xf bank_mask:0xf bound_ctrl:1
	s_and_saveexec_b64 s[16:17], s[8:9]
	s_cbranch_execz .LBB0_580
	v_cvt_pk_bf16_f32 v2, v2, v12
	v_add_co_u32_e32 v12, vcc, 0x14000, v16
	s_nop 1
	v_addc_co_u32_e32 v13, vcc, 0, v17, vcc
	global_store_dword v[12:13], v2, off offset:64
.LBB0_580:
	s_or_b64 exec, exec, s[16:17]
	v_mul_f32_e32 v2, v40, v14
	s_waitcnt lgkmcnt(0)
	s_nop 1
	v_mov_b32_dpp v12, v2 quad_perm:[1,0,3,2] row_mask:0xf bank_mask:0xf bound_ctrl:1
	s_and_saveexec_b64 s[16:17], s[8:9]
	s_cbranch_execz .LBB0_582
	v_cvt_pk_bf16_f32 v2, v2, v12
	v_add_co_u32_e32 v12, vcc, 0x14000, v16
	s_nop 1
	v_addc_co_u32_e32 v13, vcc, 0, v17, vcc
	global_store_dword v[12:13], v2, off offset:128
.LBB0_582:
	s_or_b64 exec, exec, s[16:17]
	v_mul_f32_e32 v2, v24, v14
	s_waitcnt lgkmcnt(0)
	s_nop 1
	v_mov_b32_dpp v12, v2 quad_perm:[1,0,3,2] row_mask:0xf bank_mask:0xf bound_ctrl:1
	s_and_saveexec_b64 s[16:17], s[8:9]
	s_cbranch_execz .LBB0_584
	v_cvt_pk_bf16_f32 v2, v2, v12
	v_add_co_u32_e32 v12, vcc, 0x14000, v16
	s_nop 1
	v_addc_co_u32_e32 v13, vcc, 0, v17, vcc
	global_store_dword v[12:13], v2, off offset:192
.LBB0_584:
	s_or_b64 exec, exec, s[16:17]
	v_mul_f32_e32 v2, v73, v15
	s_waitcnt lgkmcnt(0)
	s_nop 1
	v_mov_b32_dpp v12, v2 quad_perm:[1,0,3,2] row_mask:0xf bank_mask:0xf bound_ctrl:1
	s_and_saveexec_b64 s[16:17], s[8:9]
	s_cbranch_execz .LBB0_586
	v_cvt_pk_bf16_f32 v2, v2, v12
	v_add_co_u32_e32 v12, vcc, 0x16000, v16
	s_nop 1
	v_addc_co_u32_e32 v13, vcc, 0, v17, vcc
	global_store_dword v[12:13], v2, off
.LBB0_586:
	s_or_b64 exec, exec, s[16:17]
	v_mul_f32_e32 v2, v57, v15
	s_waitcnt lgkmcnt(0)
	s_nop 1
	v_mov_b32_dpp v12, v2 quad_perm:[1,0,3,2] row_mask:0xf bank_mask:0xf bound_ctrl:1
	s_and_saveexec_b64 s[16:17], s[8:9]
	s_cbranch_execz .LBB0_588
	v_cvt_pk_bf16_f32 v2, v2, v12
	v_add_co_u32_e32 v12, vcc, 0x16000, v16
	s_nop 1
	v_addc_co_u32_e32 v13, vcc, 0, v17, vcc
	global_store_dword v[12:13], v2, off offset:64
.LBB0_588:
	s_or_b64 exec, exec, s[16:17]
	v_mul_f32_e32 v2, v41, v15
	s_waitcnt lgkmcnt(0)
	s_nop 1
	v_mov_b32_dpp v12, v2 quad_perm:[1,0,3,2] row_mask:0xf bank_mask:0xf bound_ctrl:1
	s_and_saveexec_b64 s[16:17], s[8:9]
	s_cbranch_execz .LBB0_590
	v_cvt_pk_bf16_f32 v2, v2, v12
	v_add_co_u32_e32 v12, vcc, 0x16000, v16
	s_nop 1
	v_addc_co_u32_e32 v13, vcc, 0, v17, vcc
	global_store_dword v[12:13], v2, off offset:128
.LBB0_590:
	s_or_b64 exec, exec, s[16:17]
	v_mul_f32_e32 v2, v25, v15
	s_waitcnt lgkmcnt(0)
	s_nop 1
	v_mov_b32_dpp v12, v2 quad_perm:[1,0,3,2] row_mask:0xf bank_mask:0xf bound_ctrl:1
	s_and_saveexec_b64 s[16:17], s[8:9]
	s_cbranch_execz .LBB0_592
	v_cvt_pk_bf16_f32 v2, v2, v12
	v_add_co_u32_e32 v12, vcc, 0x16000, v16
	s_nop 1
	v_addc_co_u32_e32 v13, vcc, 0, v17, vcc
	global_store_dword v[12:13], v2, off offset:192
.LBB0_592:
	s_or_b64 exec, exec, s[16:17]
	v_mul_f32_e32 v2, v74, v8
	s_waitcnt lgkmcnt(0)
	s_nop 1
	v_mov_b32_dpp v12, v2 quad_perm:[1,0,3,2] row_mask:0xf bank_mask:0xf bound_ctrl:1
	s_and_saveexec_b64 s[16:17], s[8:9]
	s_cbranch_execz .LBB0_594
	v_cvt_pk_bf16_f32 v2, v2, v12
	v_add_co_u32_e32 v12, vcc, 0x20000, v16
	s_nop 1
	v_addc_co_u32_e32 v13, vcc, 0, v17, vcc
	global_store_dword v[12:13], v2, off
.LBB0_594:
	s_or_b64 exec, exec, s[16:17]
	v_mul_f32_e32 v2, v58, v8
	s_waitcnt lgkmcnt(0)
	s_nop 1
	v_mov_b32_dpp v12, v2 quad_perm:[1,0,3,2] row_mask:0xf bank_mask:0xf bound_ctrl:1
	s_and_saveexec_b64 s[16:17], s[8:9]
	s_cbranch_execz .LBB0_596
	v_cvt_pk_bf16_f32 v2, v2, v12
	v_add_co_u32_e32 v12, vcc, 0x20000, v16
	s_nop 1
	v_addc_co_u32_e32 v13, vcc, 0, v17, vcc
	global_store_dword v[12:13], v2, off offset:64
.LBB0_596:
	s_or_b64 exec, exec, s[16:17]
	v_mul_f32_e32 v2, v42, v8
	s_waitcnt lgkmcnt(0)
	s_nop 1
	v_mov_b32_dpp v12, v2 quad_perm:[1,0,3,2] row_mask:0xf bank_mask:0xf bound_ctrl:1
	s_and_saveexec_b64 s[16:17], s[8:9]
	s_cbranch_execz .LBB0_598
	v_cvt_pk_bf16_f32 v2, v2, v12
	v_add_co_u32_e32 v12, vcc, 0x20000, v16
	s_nop 1
	v_addc_co_u32_e32 v13, vcc, 0, v17, vcc
	global_store_dword v[12:13], v2, off offset:128

.LBB0_600:
	s_or_b64 exec, exec, s[16:17]
	v_mul_f32_e32 v2, v75, v9
	s_waitcnt lgkmcnt(0)
	s_nop 1
	v_mov_b32_dpp v8, v2 quad_perm:[1,0,3,2] row_mask:0xf bank_mask:0xf bound_ctrl:1
	s_and_saveexec_b64 s[16:17], s[8:9]
	s_cbranch_execz .LBB0_602
	v_add_co_u32_e32 v12, vcc, 0x22000, v16
	v_cvt_pk_bf16_f32 v2, v2, v8
	s_nop 0
	v_addc_co_u32_e32 v13, vcc, 0, v17, vcc
	global_store_dword v[12:13], v2, off
.LBB0_602:
	s_or_b64 exec, exec, s[16:17]
	v_mul_f32_e32 v2, v59, v9
	s_waitcnt lgkmcnt(0)
	s_nop 1
	v_mov_b32_dpp v8, v2 quad_perm:[1,0,3,2] row_mask:0xf bank_mask:0xf bound_ctrl:1
	s_and_saveexec_b64 s[16:17], s[8:9]
	s_cbranch_execz .LBB0_604
	v_add_co_u32_e32 v12, vcc, 0x22000, v16
	v_cvt_pk_bf16_f32 v2, v2, v8
	s_nop 0
	v_addc_co_u32_e32 v13, vcc, 0, v17, vcc
	global_store_dword v[12:13], v2, off offset:64
.LBB0_604:
	s_or_b64 exec, exec, s[16:17]
	v_mul_f32_e32 v2, v43, v9
	s_waitcnt lgkmcnt(0)
	s_nop 1
	v_mov_b32_dpp v8, v2 quad_perm:[1,0,3,2] row_mask:0xf bank_mask:0xf bound_ctrl:1
	s_and_saveexec_b64 s[16:17], s[8:9]
	s_cbranch_execz .LBB0_606
	v_add_co_u32_e32 v12, vcc, 0x22000, v16
	v_cvt_pk_bf16_f32 v2, v2, v8
	s_nop 0
	v_addc_co_u32_e32 v13, vcc, 0, v17, vcc
	global_store_dword v[12:13], v2, off offset:128
.LBB0_606:
	s_or_b64 exec, exec, s[16:17]
	v_mul_f32_e32 v2, v27, v9
	s_waitcnt lgkmcnt(0)
	s_nop 1
	v_mov_b32_dpp v8, v2 quad_perm:[1,0,3,2] row_mask:0xf bank_mask:0xf bound_ctrl:1
	s_and_saveexec_b64 s[16:17], s[8:9]
	s_cbranch_execz .LBB0_608
	v_cvt_pk_bf16_f32 v2, v2, v8
	v_add_co_u32_e32 v8, vcc, 0x22000, v16
	s_nop 1
	v_addc_co_u32_e32 v9, vcc, 0, v17, vcc
	global_store_dword v[8:9], v2, off offset:192
.LBB0_608:
	s_or_b64 exec, exec, s[16:17]
	v_mul_f32_e32 v2, v76, v10
	s_waitcnt lgkmcnt(0)
	s_nop 1
	v_mov_b32_dpp v8, v2 quad_perm:[1,0,3,2] row_mask:0xf bank_mask:0xf bound_ctrl:1
	s_and_saveexec_b64 s[16:17], s[8:9]
	s_cbranch_execz .LBB0_610
	v_cvt_pk_bf16_f32 v2, v2, v8
	v_add_co_u32_e32 v8, vcc, 0x24000, v16
	s_nop 1
	v_addc_co_u32_e32 v9, vcc, 0, v17, vcc
	global_store_dword v[8:9], v2, off
.LBB0_610:
	s_or_b64 exec, exec, s[16:17]
	v_mul_f32_e32 v2, v60, v10
	s_waitcnt lgkmcnt(0)
	s_nop 1
	v_mov_b32_dpp v8, v2 quad_perm:[1,0,3,2] row_mask:0xf bank_mask:0xf bound_ctrl:1
	s_and_saveexec_b64 s[16:17], s[8:9]
	s_cbranch_execz .LBB0_612
	v_cvt_pk_bf16_f32 v2, v2, v8
	v_add_co_u32_e32 v8, vcc, 0x24000, v16
	s_nop 1
	v_addc_co_u32_e32 v9, vcc, 0, v17, vcc
	global_store_dword v[8:9], v2, off offset:64
.LBB0_612:
	s_or_b64 exec, exec, s[16:17]
	v_mul_f32_e32 v2, v44, v10
	s_waitcnt lgkmcnt(0)
	s_nop 1
	v_mov_b32_dpp v8, v2 quad_perm:[1,0,3,2] row_mask:0xf bank_mask:0xf bound_ctrl:1
	s_and_saveexec_b64 s[16:17], s[8:9]
	s_cbranch_execz .LBB0_614
	v_cvt_pk_bf16_f32 v2, v2, v8
	v_add_co_u32_e32 v8, vcc, 0x24000, v16
	s_nop 1
	v_addc_co_u32_e32 v9, vcc, 0, v17, vcc
	global_store_dword v[8:9], v2, off offset:128
.LBB0_614:
	s_or_b64 exec, exec, s[16:17]
	v_mul_f32_e32 v2, v28, v10
	s_waitcnt lgkmcnt(0)
	s_nop 1
	v_mov_b32_dpp v8, v2 quad_perm:[1,0,3,2] row_mask:0xf bank_mask:0xf bound_ctrl:1
	s_and_saveexec_b64 s[16:17], s[8:9]
	s_cbranch_execz .LBB0_616
	v_cvt_pk_bf16_f32 v2, v2, v8
	v_add_co_u32_e32 v8, vcc, 0x24000, v16
	s_nop 1
	v_addc_co_u32_e32 v9, vcc, 0, v17, vcc
	global_store_dword v[8:9], v2, off offset:192
.LBB0_616:
	s_or_b64 exec, exec, s[16:17]
	v_mul_f32_e32 v2, v77, v11
	s_waitcnt lgkmcnt(0)
	s_nop 1
	v_mov_b32_dpp v8, v2 quad_perm:[1,0,3,2] row_mask:0xf bank_mask:0xf bound_ctrl:1
	s_and_saveexec_b64 s[16:17], s[8:9]
	s_cbranch_execz .LBB0_618
	v_cvt_pk_bf16_f32 v2, v2, v8
	v_add_co_u32_e32 v8, vcc, 0x26000, v16
	s_nop 1
	v_addc_co_u32_e32 v9, vcc, 0, v17, vcc
	global_store_dword v[8:9], v2, off
.LBB0_618:
	s_or_b64 exec, exec, s[16:17]
	v_mul_f32_e32 v2, v61, v11
	s_waitcnt lgkmcnt(0)
	s_nop 1
	v_mov_b32_dpp v8, v2 quad_perm:[1,0,3,2] row_mask:0xf bank_mask:0xf bound_ctrl:1
	s_and_saveexec_b64 s[16:17], s[8:9]
	s_cbranch_execz .LBB0_620
	v_cvt_pk_bf16_f32 v2, v2, v8
	v_add_co_u32_e32 v8, vcc, 0x26000, v16
	s_nop 1
	v_addc_co_u32_e32 v9, vcc, 0, v17, vcc
	global_store_dword v[8:9], v2, off offset:64
.LBB0_620:
	s_or_b64 exec, exec, s[16:17]
	v_mul_f32_e32 v2, v45, v11
	s_waitcnt lgkmcnt(0)
	s_nop 1
	v_mov_b32_dpp v8, v2 quad_perm:[1,0,3,2] row_mask:0xf bank_mask:0xf bound_ctrl:1
	s_and_saveexec_b64 s[16:17], s[8:9]
	s_cbranch_execz .LBB0_622
	v_cvt_pk_bf16_f32 v2, v2, v8
	v_add_co_u32_e32 v8, vcc, 0x26000, v16
	s_nop 1
	v_addc_co_u32_e32 v9, vcc, 0, v17, vcc
	global_store_dword v[8:9], v2, off offset:128
.LBB0_622:
	s_or_b64 exec, exec, s[16:17]
	v_mul_f32_e32 v2, v29, v11
	s_waitcnt lgkmcnt(0)
	s_nop 1
	v_mov_b32_dpp v8, v2 quad_perm:[1,0,3,2] row_mask:0xf bank_mask:0xf bound_ctrl:1
	s_and_saveexec_b64 s[16:17], s[8:9]
	s_cbranch_execz .LBB0_624
	v_cvt_pk_bf16_f32 v2, v2, v8
	v_add_co_u32_e32 v8, vcc, 0x26000, v16
	s_nop 1
	v_addc_co_u32_e32 v9, vcc, 0, v17, vcc
	global_store_dword v[8:9], v2, off offset:192
.LBB0_624:
	s_or_b64 exec, exec, s[16:17]
	v_mul_f32_e32 v2, v78, v4
	s_waitcnt lgkmcnt(0)
	s_nop 1
	v_mov_b32_dpp v8, v2 quad_perm:[1,0,3,2] row_mask:0xf bank_mask:0xf bound_ctrl:1
	s_and_saveexec_b64 s[16:17], s[8:9]
	s_cbranch_execz .LBB0_626
	v_cvt_pk_bf16_f32 v2, v2, v8
	v_add_co_u32_e32 v8, vcc, 0x30000, v16
	s_nop 1
	v_addc_co_u32_e32 v9, vcc, 0, v17, vcc
	global_store_dword v[8:9], v2, off
.LBB0_626:
	s_or_b64 exec, exec, s[16:17]
	v_mul_f32_e32 v2, v62, v4
	s_waitcnt lgkmcnt(0)
	s_nop 1
	v_mov_b32_dpp v8, v2 quad_perm:[1,0,3,2] row_mask:0xf bank_mask:0xf bound_ctrl:1
	s_and_saveexec_b64 s[16:17], s[8:9]
	s_cbranch_execz .LBB0_628
	v_cvt_pk_bf16_f32 v2, v2, v8
	v_add_co_u32_e32 v8, vcc, 0x30000, v16
	s_nop 1
	v_addc_co_u32_e32 v9, vcc, 0, v17, vcc
	global_store_dword v[8:9], v2, off offset:64
.LBB0_628:
	s_or_b64 exec, exec, s[16:17]
	v_mul_f32_e32 v2, v46, v4
	s_waitcnt lgkmcnt(0)
	s_nop 1
	v_mov_b32_dpp v8, v2 quad_perm:[1,0,3,2] row_mask:0xf bank_mask:0xf bound_ctrl:1
	s_and_saveexec_b64 s[16:17], s[8:9]
	s_cbranch_execz .LBB0_630
	v_cvt_pk_bf16_f32 v2, v2, v8
	v_add_co_u32_e32 v8, vcc, 0x30000, v16
	s_nop 1
	v_addc_co_u32_e32 v9, vcc, 0, v17, vcc
	global_store_dword v[8:9], v2, off offset:128

.LBB0_632:
	s_or_b64 exec, exec, s[16:17]
	v_mul_f32_e32 v2, v79, v5
	s_waitcnt lgkmcnt(0)
	s_nop 1
	v_mov_b32_dpp v4, v2 quad_perm:[1,0,3,2] row_mask:0xf bank_mask:0xf bound_ctrl:1
	s_and_saveexec_b64 s[16:17], s[8:9]
	s_cbranch_execz .LBB0_634
	v_add_co_u32_e32 v8, vcc, 0x32000, v16
	v_cvt_pk_bf16_f32 v2, v2, v4
	s_nop 0
	v_addc_co_u32_e32 v9, vcc, 0, v17, vcc
	global_store_dword v[8:9], v2, off
.LBB0_634:
	s_or_b64 exec, exec, s[16:17]
	v_mul_f32_e32 v2, v63, v5
	s_waitcnt lgkmcnt(0)
	s_nop 1
	v_mov_b32_dpp v4, v2 quad_perm:[1,0,3,2] row_mask:0xf bank_mask:0xf bound_ctrl:1
	s_and_saveexec_b64 s[16:17], s[8:9]
	s_cbranch_execz .LBB0_636
	v_add_co_u32_e32 v8, vcc, 0x32000, v16
	v_cvt_pk_bf16_f32 v2, v2, v4
	s_nop 0
	v_addc_co_u32_e32 v9, vcc, 0, v17, vcc
	global_store_dword v[8:9], v2, off offset:64
.LBB0_636:
	s_or_b64 exec, exec, s[16:17]
	v_mul_f32_e32 v2, v47, v5
	s_waitcnt lgkmcnt(0)
	s_nop 1
	v_mov_b32_dpp v4, v2 quad_perm:[1,0,3,2] row_mask:0xf bank_mask:0xf bound_ctrl:1
	s_and_saveexec_b64 s[16:17], s[8:9]
	s_cbranch_execz .LBB0_638
	v_add_co_u32_e32 v8, vcc, 0x32000, v16
	v_cvt_pk_bf16_f32 v2, v2, v4
	s_nop 0
	v_addc_co_u32_e32 v9, vcc, 0, v17, vcc
	global_store_dword v[8:9], v2, off offset:128
.LBB0_638:
	s_or_b64 exec, exec, s[16:17]
	v_mul_f32_e32 v2, v31, v5
	s_waitcnt lgkmcnt(0)
	s_nop 1
	v_mov_b32_dpp v4, v2 quad_perm:[1,0,3,2] row_mask:0xf bank_mask:0xf bound_ctrl:1
	s_and_saveexec_b64 s[16:17], s[8:9]
	s_cbranch_execz .LBB0_640
	v_cvt_pk_bf16_f32 v2, v2, v4
	v_add_co_u32_e32 v4, vcc, 0x32000, v16
	s_nop 1
	v_addc_co_u32_e32 v5, vcc, 0, v17, vcc
	global_store_dword v[4:5], v2, off offset:192
.LBB0_640:
	s_or_b64 exec, exec, s[16:17]
	v_mul_f32_e32 v2, v80, v6
	s_waitcnt lgkmcnt(0)
	s_nop 1
	v_mov_b32_dpp v4, v2 quad_perm:[1,0,3,2] row_mask:0xf bank_mask:0xf bound_ctrl:1
	s_and_saveexec_b64 s[16:17], s[8:9]
	s_cbranch_execz .LBB0_642
	v_cvt_pk_bf16_f32 v2, v2, v4
	v_add_co_u32_e32 v4, vcc, 0x34000, v16
	s_nop 1
	v_addc_co_u32_e32 v5, vcc, 0, v17, vcc
	global_store_dword v[4:5], v2, off
.LBB0_642:
	s_or_b64 exec, exec, s[16:17]
	v_mul_f32_e32 v2, v64, v6
	s_waitcnt lgkmcnt(0)
	s_nop 1
	v_mov_b32_dpp v4, v2 quad_perm:[1,0,3,2] row_mask:0xf bank_mask:0xf bound_ctrl:1
	s_and_saveexec_b64 s[16:17], s[8:9]
	s_cbranch_execz .LBB0_644
	v_cvt_pk_bf16_f32 v2, v2, v4
	v_add_co_u32_e32 v4, vcc, 0x34000, v16
	s_nop 1
	v_addc_co_u32_e32 v5, vcc, 0, v17, vcc
	global_store_dword v[4:5], v2, off offset:64
.LBB0_644:
	s_or_b64 exec, exec, s[16:17]
	v_mul_f32_e32 v2, v48, v6
	s_waitcnt lgkmcnt(0)
	s_nop 1
	v_mov_b32_dpp v4, v2 quad_perm:[1,0,3,2] row_mask:0xf bank_mask:0xf bound_ctrl:1
	s_and_saveexec_b64 s[16:17], s[8:9]
	s_cbranch_execz .LBB0_646
	v_cvt_pk_bf16_f32 v2, v2, v4
	v_add_co_u32_e32 v4, vcc, 0x34000, v16
	s_nop 1
	v_addc_co_u32_e32 v5, vcc, 0, v17, vcc
	global_store_dword v[4:5], v2, off offset:128
.LBB0_646:
	s_or_b64 exec, exec, s[16:17]
	v_mul_f32_e32 v2, v32, v6
	s_waitcnt lgkmcnt(0)
	s_nop 1
	v_mov_b32_dpp v4, v2 quad_perm:[1,0,3,2] row_mask:0xf bank_mask:0xf bound_ctrl:1
	s_and_saveexec_b64 s[16:17], s[8:9]
	s_cbranch_execz .LBB0_648
	v_cvt_pk_bf16_f32 v2, v2, v4
	v_add_co_u32_e32 v4, vcc, 0x34000, v16
	s_nop 1
	v_addc_co_u32_e32 v5, vcc, 0, v17, vcc
	global_store_dword v[4:5], v2, off offset:192
.LBB0_648:
	s_or_b64 exec, exec, s[16:17]
	v_mul_f32_e32 v2, v81, v7
	s_waitcnt lgkmcnt(0)
	s_nop 1
	v_mov_b32_dpp v4, v2 quad_perm:[1,0,3,2] row_mask:0xf bank_mask:0xf bound_ctrl:1
	s_and_saveexec_b64 s[16:17], s[8:9]
	s_cbranch_execz .LBB0_650
	v_cvt_pk_bf16_f32 v2, v2, v4
	v_add_co_u32_e32 v4, vcc, 0x36000, v16
	s_nop 1
	v_addc_co_u32_e32 v5, vcc, 0, v17, vcc
	global_store_dword v[4:5], v2, off
.LBB0_650:
	s_or_b64 exec, exec, s[16:17]
	v_mul_f32_e32 v2, v65, v7
	s_waitcnt lgkmcnt(0)
	s_nop 1
	v_mov_b32_dpp v4, v2 quad_perm:[1,0,3,2] row_mask:0xf bank_mask:0xf bound_ctrl:1
	s_and_saveexec_b64 s[16:17], s[8:9]
	s_cbranch_execz .LBB0_652
	v_cvt_pk_bf16_f32 v2, v2, v4
	v_add_co_u32_e32 v4, vcc, 0x36000, v16
	s_nop 1
	v_addc_co_u32_e32 v5, vcc, 0, v17, vcc
	global_store_dword v[4:5], v2, off offset:64
.LBB0_652:
	s_or_b64 exec, exec, s[16:17]
	v_mul_f32_e32 v2, v49, v7
	s_waitcnt lgkmcnt(0)
	s_nop 1
	v_mov_b32_dpp v4, v2 quad_perm:[1,0,3,2] row_mask:0xf bank_mask:0xf bound_ctrl:1
	s_and_saveexec_b64 s[16:17], s[8:9]
	s_cbranch_execz .LBB0_654
	v_cvt_pk_bf16_f32 v2, v2, v4
	v_add_co_u32_e32 v4, vcc, 0x36000, v16
	s_nop 1
	v_addc_co_u32_e32 v5, vcc, 0, v17, vcc
	global_store_dword v[4:5], v2, off offset:128
.LBB0_654:
	s_or_b64 exec, exec, s[16:17]
	v_mul_f32_e32 v2, v33, v7
	s_waitcnt lgkmcnt(0)
	s_nop 1
	v_mov_b32_dpp v4, v2 quad_perm:[1,0,3,2] row_mask:0xf bank_mask:0xf bound_ctrl:1
	s_and_saveexec_b64 s[16:17], s[8:9]
	s_cbranch_execz .LBB0_495
	v_cvt_pk_bf16_f32 v2, v2, v4
	v_add_co_u32_e32 v4, vcc, 0x36000, v16
	s_nop 1
	v_addc_co_u32_e32 v5, vcc, 0, v17, vcc
	global_store_dword v[4:5], v2, off offset:192
	s_branch .LBB0_495

.LBB0_1517:
	s_or_b64 exec, exec, s[8:9]
	v_ashrrev_i32_e32 v89, 5, v16
	v_lshlrev_b32_e32 v17, 4, v89
	v_and_b32_e32 v88, 1, v16
	s_waitcnt lgkmcnt(0)
	s_waitcnt vmcnt(1)
	v_add_u32_e32 v4, s33, v17
	v_cmp_eq_u32_e32 vcc, 0, v88
	v_lshlrev_b32_e32 v88, 15, v89
	ds_read_b128 v[82:85], v4
	ds_read_b128 v[12:15], v4 offset:32
	ds_read_b128 v[8:11], v4 offset:64
	s_waitcnt vmcnt(0)
	ds_read_b128 v[4:7], v4 offset:96
	v_and_b32_e32 v88, 0x8000, v88
	s_add_i32 s2, 0, 0x14800
	v_lshrrev_b32_e32 v90, 6, v16
	s_waitcnt lgkmcnt(0)
	v_add_u32_e32 v88, s2, v88
	v_add_u32_e32 v90, s81, v90
	v_lshlrev_b32_e32 v87, 1, v2
	v_lshl_add_u32 v92, v90, 8, v88
	v_mul_f32_e32 v90, v66, v82
	v_add_u32_e32 v66, v92, v87
	s_nop 0
	v_mov_b32_dpp v91, v90 quad_perm:[1,0,3,2] row_mask:0xf bank_mask:0xf bound_ctrl:1
	s_and_saveexec_b64 s[8:9], vcc
	v_readlane_b32 s96, v250, 35
	s_cbranch_execz .LBB0_1519
	v_cvt_pk_bf16_f32 v90, v90, v91
	ds_write_b32 v66, v90

.LBB0_1774:
	s_or_b64 exec, exec, s[10:11]
	s_waitcnt vmcnt(1)
	v_ashrrev_i32_e32 v2, 5, v16
	s_waitcnt lgkmcnt(0)
	s_waitcnt vmcnt(0)
	v_lshl_add_u32 v4, v2, 4, s33
	ds_read_b128 v[82:85], v4
	ds_read_b128 v[12:15], v4 offset:32
	ds_read_b128 v[8:11], v4 offset:64
	ds_read_b128 v[4:7], v4 offset:96
	s_waitcnt lgkmcnt(0)
	v_lshlrev_b32_e32 v17, 1, v16
	v_and_b32_e32 v16, 1, v16
	v_lshlrev_b32_e32 v2, 10, v2
	v_and_b32_e32 v17, 60, v17
	v_cmp_eq_u32_e32 vcc, 0, v16
	v_mul_f32_e32 v16, v66, v82
	v_add3_u32 v2, s83, v2, v17
	s_nop 0
	v_mov_b32_dpp v17, v16 quad_perm:[1,0,3,2] row_mask:0xf bank_mask:0xf bound_ctrl:1
	s_and_saveexec_b64 s[10:11], vcc
	s_cbranch_execz .LBB0_1776
	ds_read_b32 v66, v2
	s_waitcnt lgkmcnt(0)
	v_lshlrev_b32_e32 v86, 16, v66
	v_and_b32_e32 v66, 0xffff0000, v66
	v_add_f32_e32 v16, v16, v86
	v_add_f32_e32 v17, v17, v66
	v_cvt_pk_bf16_f32 v16, v16, v17
	ds_write_b32 v2, v16

.LBB0_2434:
	s_waitcnt vmcnt(7)
	v_cvt_f32_f16_sdwa v73, v2 dst_sel:DWORD dst_unused:UNUSED_PAD src0_sel:WORD_1
	v_cvt_f32_f16_e32 v72, v2
	v_cvt_f32_f16_sdwa v77, v4 dst_sel:DWORD dst_unused:UNUSED_PAD src0_sel:WORD_1
	v_cvt_f32_f16_e32 v76, v4
	v_cvt_f32_f16_sdwa v75, v3 dst_sel:DWORD dst_unused:UNUSED_PAD src0_sel:WORD_1
	v_cvt_f32_f16_e32 v74, v3
	v_cvt_f32_f16_sdwa v79, v5 dst_sel:DWORD dst_unused:UNUSED_PAD src0_sel:WORD_1
	v_cvt_f32_f16_e32 v78, v5
	v_mov_b32_e32 v2, v72
	v_mov_b32_e32 v3, v76
	v_mov_b32_e32 v4, v73
	v_mov_b32_e32 v5, v77
	v_pk_add_f32 v[2:3], v[2:3], v[4:5]
	v_mov_b32_e32 v4, v74
	v_mov_b32_e32 v5, v78
	v_mov_b32_e32 v80, v75
	v_mov_b32_e32 v81, v79
	v_pk_add_f32 v[4:5], v[4:5], v[80:81]
	s_waitcnt vmcnt(6)
	v_cvt_f32_f16_e32 v80, v6
	v_cvt_f32_f16_e32 v82, v7
	v_cvt_f32_f16_sdwa v81, v6 dst_sel:DWORD dst_unused:UNUSED_PAD src0_sel:WORD_1
	v_cvt_f32_f16_sdwa v83, v7 dst_sel:DWORD dst_unused:UNUSED_PAD src0_sel:WORD_1
	v_cvt_f32_f16_e32 v84, v8
	v_cvt_f32_f16_e32 v86, v9
	v_cvt_f32_f16_sdwa v85, v8 dst_sel:DWORD dst_unused:UNUSED_PAD src0_sel:WORD_1
	v_cvt_f32_f16_sdwa v87, v9 dst_sel:DWORD dst_unused:UNUSED_PAD src0_sel:WORD_1
	s_waitcnt vmcnt(5)
	v_cvt_f32_f16_sdwa v93, v12 dst_sel:DWORD dst_unused:UNUSED_PAD src0_sel:WORD_1
	v_cvt_f32_f16_sdwa v95, v13 dst_sel:DWORD dst_unused:UNUSED_PAD src0_sel:WORD_1
	v_cvt_f32_f16_e32 v92, v12
	v_cvt_f32_f16_e32 v94, v13
	v_pk_add_f32 v[2:3], v[2:3], v[4:5]
	v_mov_b32_e32 v4, v80
	v_mov_b32_e32 v5, v82
	v_mov_b32_e32 v6, v81
	v_mov_b32_e32 v7, v83
	v_cvt_f32_f16_sdwa v89, v10 dst_sel:DWORD dst_unused:UNUSED_PAD src0_sel:WORD_1
	v_cvt_f32_f16_sdwa v91, v11 dst_sel:DWORD dst_unused:UNUSED_PAD src0_sel:WORD_1
	s_waitcnt vmcnt(4)
	v_cvt_f32_f16_sdwa v101, v15 dst_sel:DWORD dst_unused:UNUSED_PAD src0_sel:WORD_1
	v_cvt_f32_f16_e32 v100, v15
	v_cvt_f32_f16_sdwa v113, v17 dst_sel:DWORD dst_unused:UNUSED_PAD src0_sel:WORD_1
	v_cvt_f32_f16_e32 v112, v17
	v_pk_add_f32 v[4:5], v[4:5], v[6:7]
	v_mov_b32_e32 v6, v84
	v_mov_b32_e32 v7, v86
	v_mov_b32_e32 v8, v85
	v_mov_b32_e32 v9, v87
	v_cvt_f32_f16_e32 v88, v10
	v_cvt_f32_f16_e32 v90, v11
	v_cvt_f32_f16_sdwa v99, v14 dst_sel:DWORD dst_unused:UNUSED_PAD src0_sel:WORD_1
	v_cvt_f32_f16_e32 v98, v14
	v_pk_add_f32 v[6:7], v[6:7], v[8:9]
	v_mov_b32_e32 v12, v93
	v_mov_b32_e32 v96, v95
	v_cvt_f32_f16_sdwa v103, v16 dst_sel:DWORD dst_unused:UNUSED_PAD src0_sel:WORD_1
	v_cvt_f32_f16_e32 v102, v16
	v_pk_add_f32 v[4:5], v[4:5], v[4:5] op_sel:[0,1] op_sel_hi:[1,0]
	v_pk_add_f32 v[6:7], v[6:7], v[6:7] op_sel:[0,1] op_sel_hi:[1,0]
	v_pk_add_f32 v[12:13], v[12:13], v[92:93]
	v_pk_add_f32 v[96:97], v[96:97], v[94:95]
	v_pk_add_f32 v[2:3], v[2:3], v[2:3] op_sel:[0,1] op_sel_hi:[1,0]
	v_mov_b32_e32 v8, v89
	v_mov_b32_e32 v10, v91
	v_mov_b32_e32 v5, v100
	v_mov_b32_e32 v7, v101
	v_mov_b32_e32 v13, v112
	v_mov_b32_e32 v97, v113
	v_pk_add_f32 v[8:9], v[8:9], v[88:89]
	v_pk_add_f32 v[10:11], v[10:11], v[90:91]
	v_mov_b32_e32 v3, v98
	v_mov_b32_e32 v37, v99
	v_pk_add_f32 v[4:5], v[4:5], v[6:7]
	v_pk_add_f32 v[6:7], v[12:13], v[96:97]
	s_waitcnt vmcnt(3)
	v_cvt_f32_f16_sdwa v97, v18 dst_sel:DWORD dst_unused:UNUSED_PAD src0_sel:WORD_1
	v_cvt_f32_f16_e32 v96, v18
	v_cvt_f32_f16_sdwa v147, v20 dst_sel:DWORD dst_unused:UNUSED_PAD src0_sel:WORD_1
	v_cvt_f32_f16_e32 v146, v20
	v_pk_add_f32 v[2:3], v[2:3], v[36:37]
	v_mov_b32_e32 v9, v102
	v_mov_b32_e32 v11, v103
	v_cvt_f32_f16_sdwa v145, v19 dst_sel:DWORD dst_unused:UNUSED_PAD src0_sel:WORD_1
	v_cvt_f32_f16_e32 v144, v19
	v_cvt_f32_f16_sdwa v149, v21 dst_sel:DWORD dst_unused:UNUSED_PAD src0_sel:WORD_1
	v_cvt_f32_f16_e32 v148, v21
	v_pk_add_f32 v[2:3], v[2:3], v[4:5]
	v_pk_add_f32 v[4:5], v[8:9], v[10:11]
	s_waitcnt vmcnt(2)
	v_cvt_f32_f16_e32 v150, v22
	v_pk_add_f32 v[4:5], v[4:5], v[6:7]
	v_cvt_f32_f16_e32 v152, v23
	v_cvt_f32_f16_sdwa v151, v22 dst_sel:DWORD dst_unused:UNUSED_PAD src0_sel:WORD_1
	v_cvt_f32_f16_sdwa v153, v23 dst_sel:DWORD dst_unused:UNUSED_PAD src0_sel:WORD_1
	v_pk_add_f32 v[2:3], v[2:3], v[4:5]
	v_mov_b32_e32 v4, v96
	v_mov_b32_e32 v5, v146
	v_mov_b32_e32 v6, v97
	v_mov_b32_e32 v7, v147
	v_cvt_f32_f16_e32 v154, v24
	v_cvt_f32_f16_e32 v156, v25
	v_cvt_f32_f16_sdwa v155, v24 dst_sel:DWORD dst_unused:UNUSED_PAD src0_sel:WORD_1
	v_cvt_f32_f16_sdwa v157, v25 dst_sel:DWORD dst_unused:UNUSED_PAD src0_sel:WORD_1
	v_pk_add_f32 v[4:5], v[4:5], v[6:7]
	v_mov_b32_e32 v6, v144
	v_mov_b32_e32 v7, v148
	v_mov_b32_e32 v8, v145
	v_mov_b32_e32 v9, v149
	v_pk_add_f32 v[6:7], v[6:7], v[8:9]
	s_waitcnt vmcnt(1)
	v_cvt_f32_f16_sdwa v159, v26 dst_sel:DWORD dst_unused:UNUSED_PAD src0_sel:WORD_1
	v_cvt_f32_f16_sdwa v161, v27 dst_sel:DWORD dst_unused:UNUSED_PAD src0_sel:WORD_1
	v_cvt_f32_f16_sdwa v163, v28 dst_sel:DWORD dst_unused:UNUSED_PAD src0_sel:WORD_1
	v_cvt_f32_f16_sdwa v165, v29 dst_sel:DWORD dst_unused:UNUSED_PAD src0_sel:WORD_1
	v_pk_add_f32 v[4:5], v[4:5], v[6:7]
	v_mov_b32_e32 v6, v150
	v_mov_b32_e32 v7, v152
	v_mov_b32_e32 v8, v151
	v_mov_b32_e32 v9, v153
	v_cvt_f32_f16_e32 v158, v26
	v_cvt_f32_f16_e32 v160, v27
	v_cvt_f32_f16_e32 v162, v28
	v_cvt_f32_f16_e32 v164, v29
	s_waitcnt vmcnt(0)
	v_cvt_f32_f16_sdwa v167, v30 dst_sel:DWORD dst_unused:UNUSED_PAD src0_sel:WORD_1
	v_cvt_f32_f16_e32 v166, v30
	v_cvt_f32_f16_sdwa v169, v31 dst_sel:DWORD dst_unused:UNUSED_PAD src0_sel:WORD_1
	v_cvt_f32_f16_e32 v168, v31
	v_pk_add_f32 v[6:7], v[6:7], v[8:9]
	v_mov_b32_e32 v8, v154
	v_mov_b32_e32 v9, v156
	v_mov_b32_e32 v10, v155
	v_mov_b32_e32 v11, v157
	v_cvt_f32_f16_sdwa v171, v32 dst_sel:DWORD dst_unused:UNUSED_PAD src0_sel:WORD_1
	v_cvt_f32_f16_e32 v170, v32
	v_cvt_f32_f16_sdwa v173, v33 dst_sel:DWORD dst_unused:UNUSED_PAD src0_sel:WORD_1
	v_cvt_f32_f16_e32 v172, v33
	v_pk_add_f32 v[8:9], v[8:9], v[10:11]
	v_pk_add_f32 v[2:3], v[2:3], v[2:3] op_sel:[0,1] op_sel_hi:[1,0]
	v_pk_add_f32 v[4:5], v[4:5], v[4:5] op_sel:[0,1] op_sel_hi:[1,0]
	v_pk_add_f32 v[6:7], v[6:7], v[6:7] op_sel:[0,1] op_sel_hi:[1,0]
	v_pk_add_f32 v[8:9], v[8:9], v[8:9] op_sel:[0,1] op_sel_hi:[1,0]
	v_mov_b32_e32 v10, v159
	v_mov_b32_e32 v12, v161
	v_mov_b32_e32 v14, v163
	v_mov_b32_e32 v16, v165
	v_pk_add_f32 v[10:11], v[10:11], v[158:159]
	v_pk_add_f32 v[12:13], v[12:13], v[160:161]
	v_pk_add_f32 v[14:15], v[14:15], v[162:163]
	v_pk_add_f32 v[16:17], v[16:17], v[164:165]
	v_mov_b32_e32 v3, v166
	v_mov_b32_e32 v5, v167
	v_mov_b32_e32 v7, v168
	v_mov_b32_e32 v9, v169
	v_pk_add_f32 v[2:3], v[2:3], v[4:5]
	v_pk_add_f32 v[4:5], v[6:7], v[8:9]
	v_mov_b32_e32 v11, v170
	v_mov_b32_e32 v13, v171
	v_mov_b32_e32 v15, v172
	v_mov_b32_e32 v17, v173
	v_pk_add_f32 v[2:3], v[2:3], v[4:5]
	v_pk_add_f32 v[4:5], v[10:11], v[12:13]
	v_pk_add_f32 v[6:7], v[14:15], v[16:17]
	s_nop 0
	v_pk_add_f32 v[4:5], v[4:5], v[6:7]
	s_nop 0
	v_pk_add_f32 v[2:3], v[2:3], v[4:5]
	v_mov_b32_e32 v4, v34
	v_add_f32_e32 v2, v2, v3
	ds_bpermute_b32 v3, v105, v2
	v_add_u32_e32 v34, s8, v4
	v_cmp_gt_i32_e32 vcc, s14, v34
	v_cmp_lt_i32_e64 s[0:1], s9, v34
	s_waitcnt lgkmcnt(0)
	v_add_f32_e32 v2, v2, v3
	ds_bpermute_b32 v3, v138, v2
	s_waitcnt lgkmcnt(0)
	v_add_f32_e32 v5, v2, v3
	ds_bpermute_b32 v6, v139, v5
	v_cndmask_b32_e32 v2, v4, v34, vcc
	v_ashrrev_i32_e32 v3, 31, v2
	v_lshlrev_b64 v[2:3], 13, v[2:3]
	v_lshl_add_u64 v[18:19], v[38:39], 0, v[2:3]
	s_waitcnt lgkmcnt(0)
	v_add_f32_e32 v20, v5, v6
	ds_bpermute_b32 v21, v140, v20
	v_add_co_u32_e32 v30, vcc, s15, v18
	global_load_dwordx4 v[2:5], v[18:19], off
	global_load_dwordx4 v[6:9], v[18:19], off offset:1024
	global_load_dwordx4 v[10:13], v[18:19], off offset:2048
	global_load_dwordx4 v[14:17], v[18:19], off offset:3072
	v_addc_co_u32_e32 v31, vcc, 0, v19, vcc
	s_waitcnt lgkmcnt(0)
	v_add_f32_e32 v20, v20, v21
	ds_bpermute_b32 v21, v141, v20
	s_andn2_b64 vcc, exec, s[10:11]
	s_waitcnt lgkmcnt(0)
	v_add_f32_e32 v37, v20, v21
	ds_bpermute_b32 v104, v142, v37
	global_load_dwordx4 v[18:21], v[30:31], off
	global_load_dwordx4 v[22:25], v[30:31], off offset:1024
	global_load_dwordx4 v[26:29], v[30:31], off offset:2048
	s_nop 0
	global_load_dwordx4 v[30:33], v[30:31], off offset:3072
	s_waitcnt lgkmcnt(0)
	v_add_f32_e32 v37, v37, v104
	v_mul_f32_e32 v104, 0x39800000, v37
	v_pk_add_f32 v[130:131], v[72:73], v[104:105] op_sel_hi:[1,0] neg_lo:[0,1] neg_hi:[0,1]
	v_pk_add_f32 v[132:133], v[74:75], v[104:105] op_sel_hi:[1,0] neg_lo:[0,1] neg_hi:[0,1]
	v_pk_mul_f32 v[174:175], v[130:131], v[130:131]
	v_pk_mul_f32 v[176:177], v[132:133], v[132:133]
	v_add_f32_e32 v37, v174, v175
	v_pk_add_f32 v[134:135], v[76:77], v[104:105] op_sel_hi:[1,0] neg_lo:[0,1] neg_hi:[0,1]
	v_add_f32_e32 v37, v176, v37
	v_pk_mul_f32 v[178:179], v[134:135], v[134:135]
	v_add_f32_e32 v37, v177, v37
	v_pk_add_f32 v[136:137], v[78:79], v[104:105] op_sel_hi:[1,0] neg_lo:[0,1] neg_hi:[0,1]
	v_add_f32_e32 v37, v178, v37
	v_pk_mul_f32 v[180:181], v[136:137], v[136:137]
	v_add_f32_e32 v37, v179, v37
	v_pk_add_f32 v[122:123], v[80:81], v[104:105] op_sel_hi:[1,0] neg_lo:[0,1] neg_hi:[0,1]
	v_add_f32_e32 v37, v180, v37
	v_pk_mul_f32 v[182:183], v[122:123], v[122:123]
	v_add_f32_e32 v37, v181, v37
	v_pk_add_f32 v[124:125], v[82:83], v[104:105] op_sel_hi:[1,0] neg_lo:[0,1] neg_hi:[0,1]
	v_add_f32_e32 v37, v182, v37
	v_pk_mul_f32 v[184:185], v[124:125], v[124:125]
	v_add_f32_e32 v37, v183, v37
	v_pk_add_f32 v[126:127], v[84:85], v[104:105] op_sel_hi:[1,0] neg_lo:[0,1] neg_hi:[0,1]
	v_add_f32_e32 v37, v184, v37
	v_pk_mul_f32 v[186:187], v[126:127], v[126:127]
	v_add_f32_e32 v37, v185, v37
	v_pk_add_f32 v[128:129], v[86:87], v[104:105] op_sel_hi:[1,0] neg_lo:[0,1] neg_hi:[0,1]
	v_add_f32_e32 v37, v186, v37
	v_pk_mul_f32 v[188:189], v[128:129], v[128:129]
	v_add_f32_e32 v37, v187, v37
	v_pk_add_f32 v[114:115], v[88:89], v[104:105] op_sel_hi:[1,0] neg_lo:[0,1] neg_hi:[0,1]
	v_add_f32_e32 v37, v188, v37
	v_pk_mul_f32 v[190:191], v[114:115], v[114:115]
	v_add_f32_e32 v37, v189, v37
	v_pk_add_f32 v[116:117], v[90:91], v[104:105] op_sel_hi:[1,0] neg_lo:[0,1] neg_hi:[0,1]
	v_add_f32_e32 v37, v190, v37
	v_pk_mul_f32 v[192:193], v[116:117], v[116:117]
	v_add_f32_e32 v37, v191, v37
	v_pk_add_f32 v[118:119], v[92:93], v[104:105] op_sel_hi:[1,0] neg_lo:[0,1] neg_hi:[0,1]
	v_add_f32_e32 v37, v192, v37
	v_pk_mul_f32 v[194:195], v[118:119], v[118:119]
	v_add_f32_e32 v37, v193, v37
	v_pk_add_f32 v[120:121], v[94:95], v[104:105] op_sel_hi:[1,0] neg_lo:[0,1] neg_hi:[0,1]
	v_add_f32_e32 v37, v194, v37
	v_pk_mul_f32 v[196:197], v[120:121], v[120:121]
	v_add_f32_e32 v37, v195, v37
	v_pk_add_f32 v[106:107], v[98:99], v[104:105] op_sel_hi:[1,0] neg_lo:[0,1] neg_hi:[0,1]
	v_add_f32_e32 v37, v196, v37
	v_pk_mul_f32 v[198:199], v[106:107], v[106:107]
	v_add_f32_e32 v37, v197, v37
	v_pk_add_f32 v[108:109], v[100:101], v[104:105] op_sel_hi:[1,0] neg_lo:[0,1] neg_hi:[0,1]
	v_add_f32_e32 v37, v198, v37
	v_pk_mul_f32 v[200:201], v[108:109], v[108:109]
	v_add_f32_e32 v37, v199, v37
	v_pk_add_f32 v[110:111], v[102:103], v[104:105] op_sel_hi:[1,0] neg_lo:[0,1] neg_hi:[0,1]
	v_add_f32_e32 v37, v200, v37
	v_pk_mul_f32 v[202:203], v[110:111], v[110:111]
	v_add_f32_e32 v37, v201, v37
	v_pk_add_f32 v[112:113], v[112:113], v[104:105] op_sel_hi:[1,0] neg_lo:[0,1] neg_hi:[0,1]
	v_add_f32_e32 v37, v202, v37
	v_pk_mul_f32 v[204:205], v[112:113], v[112:113]
	v_add_f32_e32 v37, v203, v37
	v_pk_add_f32 v[96:97], v[96:97], v[104:105] op_sel_hi:[1,0] neg_lo:[0,1] neg_hi:[0,1]
	v_add_f32_e32 v37, v204, v37
	v_pk_mul_f32 v[206:207], v[96:97], v[96:97]
	v_add_f32_e32 v37, v205, v37
	v_pk_add_f32 v[98:99], v[144:145], v[104:105] op_sel_hi:[1,0] neg_lo:[0,1] neg_hi:[0,1]
	v_add_f32_e32 v37, v206, v37
	v_pk_mul_f32 v[144:145], v[98:99], v[98:99]
	v_add_f32_e32 v37, v207, v37
	v_pk_add_f32 v[100:101], v[146:147], v[104:105] op_sel_hi:[1,0] neg_lo:[0,1] neg_hi:[0,1]
	v_add_f32_e32 v37, v144, v37
	v_pk_mul_f32 v[146:147], v[100:101], v[100:101]
	v_add_f32_e32 v37, v145, v37
	v_pk_add_f32 v[102:103], v[148:149], v[104:105] op_sel_hi:[1,0] neg_lo:[0,1] neg_hi:[0,1]
	v_add_f32_e32 v37, v146, v37
	v_pk_mul_f32 v[148:149], v[102:103], v[102:103]
	v_add_f32_e32 v37, v147, v37
	v_pk_add_f32 v[88:89], v[150:151], v[104:105] op_sel_hi:[1,0] neg_lo:[0,1] neg_hi:[0,1]
	v_add_f32_e32 v37, v148, v37
	v_pk_mul_f32 v[150:151], v[88:89], v[88:89]
	v_add_f32_e32 v37, v149, v37
	v_pk_add_f32 v[90:91], v[152:153], v[104:105] op_sel_hi:[1,0] neg_lo:[0,1] neg_hi:[0,1]
	v_add_f32_e32 v37, v150, v37
	v_pk_mul_f32 v[152:153], v[90:91], v[90:91]
	v_add_f32_e32 v37, v151, v37
	v_pk_add_f32 v[92:93], v[154:155], v[104:105] op_sel_hi:[1,0] neg_lo:[0,1] neg_hi:[0,1]
	v_add_f32_e32 v37, v152, v37
	v_pk_mul_f32 v[154:155], v[92:93], v[92:93]
	v_add_f32_e32 v37, v153, v37
	v_pk_add_f32 v[94:95], v[156:157], v[104:105] op_sel_hi:[1,0] neg_lo:[0,1] neg_hi:[0,1]
	v_add_f32_e32 v37, v154, v37
	v_pk_mul_f32 v[156:157], v[94:95], v[94:95]
	v_add_f32_e32 v37, v155, v37
	v_pk_add_f32 v[80:81], v[158:159], v[104:105] op_sel_hi:[1,0] neg_lo:[0,1] neg_hi:[0,1]
	v_add_f32_e32 v37, v156, v37
	v_pk_mul_f32 v[158:159], v[80:81], v[80:81]
	v_add_f32_e32 v37, v157, v37
	v_pk_add_f32 v[82:83], v[160:161], v[104:105] op_sel_hi:[1,0] neg_lo:[0,1] neg_hi:[0,1]
	v_add_f32_e32 v37, v158, v37
	v_pk_mul_f32 v[160:161], v[82:83], v[82:83]
	v_add_f32_e32 v37, v159, v37
	v_pk_add_f32 v[84:85], v[162:163], v[104:105] op_sel_hi:[1,0] neg_lo:[0,1] neg_hi:[0,1]
	v_add_f32_e32 v37, v160, v37
	v_pk_mul_f32 v[162:163], v[84:85], v[84:85]
	v_add_f32_e32 v37, v161, v37
	v_pk_add_f32 v[86:87], v[164:165], v[104:105] op_sel_hi:[1,0] neg_lo:[0,1] neg_hi:[0,1]
	v_add_f32_e32 v37, v162, v37
	v_pk_mul_f32 v[164:165], v[86:87], v[86:87]
	v_add_f32_e32 v37, v163, v37
	v_pk_add_f32 v[72:73], v[166:167], v[104:105] op_sel_hi:[1,0] neg_lo:[0,1] neg_hi:[0,1]
	v_add_f32_e32 v37, v164, v37
	v_pk_mul_f32 v[166:167], v[72:73], v[72:73]
	v_add_f32_e32 v37, v165, v37
	v_pk_add_f32 v[74:75], v[168:169], v[104:105] op_sel_hi:[1,0] neg_lo:[0,1] neg_hi:[0,1]
	v_add_f32_e32 v37, v166, v37
	v_pk_mul_f32 v[168:169], v[74:75], v[74:75]
	v_add_f32_e32 v37, v167, v37
	v_pk_add_f32 v[76:77], v[170:171], v[104:105] op_sel_hi:[1,0] neg_lo:[0,1] neg_hi:[0,1]
	v_add_f32_e32 v37, v168, v37
	v_pk_mul_f32 v[170:171], v[76:77], v[76:77]
	v_add_f32_e32 v37, v169, v37
	v_pk_add_f32 v[78:79], v[172:173], v[104:105] op_sel_hi:[1,0] neg_lo:[0,1] neg_hi:[0,1]
	v_add_f32_e32 v37, v170, v37
	v_pk_mul_f32 v[172:173], v[78:79], v[78:79]
	v_add_f32_e32 v37, v171, v37
	v_add_f32_e32 v37, v172, v37
	v_add_f32_e32 v37, v173, v37
	ds_bpermute_b32 v104, v105, v37
	s_waitcnt lgkmcnt(0)
	v_add_f32_e32 v37, v37, v104
	ds_bpermute_b32 v104, v138, v37
	s_waitcnt lgkmcnt(0)
	v_add_f32_e32 v37, v37, v104
	ds_bpermute_b32 v104, v139, v37
	s_waitcnt lgkmcnt(0)
	v_add_f32_e32 v37, v37, v104
	ds_bpermute_b32 v104, v140, v37
	s_waitcnt lgkmcnt(0)
	v_add_f32_e32 v37, v37, v104
	ds_bpermute_b32 v104, v141, v37
	s_waitcnt lgkmcnt(0)
	v_add_f32_e32 v37, v37, v104
	ds_bpermute_b32 v104, v142, v37
	s_cbranch_vccnz .LBB0_2433
	ds_read_b128 v[144:147], v251 offset:16
	ds_read_b128 v[148:151], v251 offset:16400
	ds_read_b128 v[152:155], v251 offset:16384
	ds_read_b128 v[156:159], v251 offset:0
	s_waitcnt lgkmcnt(0)
	v_add_f32_e32 v37, v37, v104
	v_fmamk_f32 v37, v37, 0x39800000, v35
	v_mul_f32_e32 v104, 0x4b800000, v37
	v_cmp_gt_f32_e32 vcc, s18, v37
	s_nop 1
	v_cndmask_b32_e32 v37, v37, v104, vcc
	v_rsq_f32_e32 v37, v37
	s_nop 0
	v_mul_f32_e32 v104, 0x45800000, v37
	v_cndmask_b32_e32 v104, v37, v104, vcc
	v_pk_mul_f32 v[134:135], v[134:135], v[104:105] op_sel_hi:[1,0]
	v_pk_mul_f32 v[136:137], v[136:137], v[104:105] op_sel_hi:[1,0]
	v_pk_mul_f32 v[160:161], v[130:131], v[104:105] op_sel_hi:[1,0]
	v_pk_mul_f32 v[162:163], v[132:133], v[104:105] op_sel_hi:[1,0]
	v_pk_mul_f32 v[128:129], v[128:129], v[104:105] op_sel_hi:[1,0]
	v_pk_mul_f32 v[126:127], v[126:127], v[104:105] op_sel_hi:[1,0]
	v_pk_mul_f32 v[120:121], v[120:121], v[104:105] op_sel_hi:[1,0]
	v_pk_mul_f32 v[118:119], v[118:119], v[104:105] op_sel_hi:[1,0]
	v_pk_mul_f32 v[112:113], v[112:113], v[104:105] op_sel_hi:[1,0]
	v_pk_mul_f32 v[110:111], v[110:111], v[104:105] op_sel_hi:[1,0]
	v_pk_mul_f32 v[102:103], v[102:103], v[104:105] op_sel_hi:[1,0]
	v_pk_mul_f32 v[100:101], v[100:101], v[104:105] op_sel_hi:[1,0]
	v_pk_mul_f32 v[94:95], v[94:95], v[104:105] op_sel_hi:[1,0]
	v_pk_mul_f32 v[92:93], v[92:93], v[104:105] op_sel_hi:[1,0]
	v_pk_mul_f32 v[86:87], v[86:87], v[104:105] op_sel_hi:[1,0]
	v_pk_mul_f32 v[84:85], v[84:85], v[104:105] op_sel_hi:[1,0]
	v_pk_mul_f32 v[78:79], v[78:79], v[104:105] op_sel_hi:[1,0]
	v_pk_mul_f32 v[76:77], v[76:77], v[104:105] op_sel_hi:[1,0]
	v_pk_fma_f32 v[132:133], v[136:137], v[146:147], v[150:151]
	v_pk_fma_f32 v[130:131], v[134:135], v[144:145], v[148:149]
	v_pk_fma_f32 v[136:137], v[162:163], v[158:159], v[154:155]
	v_pk_fma_f32 v[134:135], v[160:161], v[156:157], v[152:153]
	global_store_dwordx4 v[0:1], v[134:137], off
	global_store_dwordx4 v[0:1], v[130:133], off offset:16
	ds_read_b128 v[130:133], v251 offset:2064
	s_nop 0
	ds_read_b128 v[134:137], v251 offset:18448
	ds_read_b128 v[144:147], v251 offset:18432
	ds_read_b128 v[148:151], v251 offset:2048
	v_pk_mul_f32 v[152:153], v[124:125], v[104:105] op_sel_hi:[1,0]
	v_pk_mul_f32 v[154:155], v[122:123], v[104:105] op_sel_hi:[1,0]
	s_waitcnt lgkmcnt(2)
	v_pk_fma_f32 v[122:123], v[126:127], v[130:131], v[134:135]
	v_pk_fma_f32 v[124:125], v[128:129], v[132:133], v[136:137]
	s_waitcnt lgkmcnt(0)
	v_pk_fma_f32 v[126:127], v[154:155], v[148:149], v[144:145]
	v_pk_fma_f32 v[128:129], v[152:153], v[150:151], v[146:147]
	global_store_dwordx4 v[0:1], v[126:129], off offset:2048
	global_store_dwordx4 v[0:1], v[122:125], off offset:2064
	ds_read_b128 v[122:125], v251 offset:4112
	s_nop 0
	ds_read_b128 v[126:129], v251 offset:20496
	ds_read_b128 v[130:133], v251 offset:20480
	ds_read_b128 v[134:137], v251 offset:4096
	v_add_co_u32_e32 v144, vcc, s15, v0
	v_pk_mul_f32 v[148:149], v[116:117], v[104:105] op_sel_hi:[1,0]
	s_nop 0
	v_addc_co_u32_e32 v145, vcc, 0, v1, vcc
	v_add_co_u32_e32 v146, vcc, s16, v0
	v_pk_mul_f32 v[150:151], v[114:115], v[104:105] op_sel_hi:[1,0]
	s_nop 0
	v_addc_co_u32_e32 v147, vcc, 0, v1, vcc
	s_waitcnt lgkmcnt(2)
	v_pk_fma_f32 v[114:115], v[118:119], v[122:123], v[126:127]
	v_pk_fma_f32 v[116:117], v[120:121], v[124:125], v[128:129]
	s_waitcnt lgkmcnt(0)
	v_pk_fma_f32 v[118:119], v[150:151], v[134:135], v[130:131]
	v_pk_fma_f32 v[120:121], v[148:149], v[136:137], v[132:133]
	global_store_dwordx4 v[146:147], v[118:121], off offset:-4096
	global_store_dwordx4 v[144:145], v[114:117], off offset:16
	ds_read_b128 v[114:117], v251 offset:6160
	s_nop 0
	ds_read_b128 v[118:121], v251 offset:22544
	ds_read_b128 v[122:125], v251 offset:22528
	ds_read_b128 v[126:129], v251 offset:6144
	v_pk_mul_f32 v[130:131], v[108:109], v[104:105] op_sel_hi:[1,0]
	v_pk_mul_f32 v[132:133], v[106:107], v[104:105] op_sel_hi:[1,0]
	s_waitcnt lgkmcnt(2)
	v_pk_fma_f32 v[106:107], v[110:111], v[114:115], v[118:119]
	v_pk_fma_f32 v[108:109], v[112:113], v[116:117], v[120:121]
	s_waitcnt lgkmcnt(0)
	v_pk_fma_f32 v[110:111], v[132:133], v[126:127], v[122:123]
	v_pk_fma_f32 v[112:113], v[130:131], v[128:129], v[124:125]
	global_store_dwordx4 v[144:145], v[110:113], off offset:2048
	global_store_dwordx4 v[144:145], v[106:109], off offset:2064
	ds_read_b128 v[106:109], v251 offset:8208
	s_nop 0
	ds_read_b128 v[110:113], v251 offset:24592
	ds_read_b128 v[114:117], v251 offset:24576
	ds_read_b128 v[118:121], v251 offset:8192
	v_pk_mul_f32 v[122:123], v[98:99], v[104:105] op_sel_hi:[1,0]
	v_pk_mul_f32 v[124:125], v[96:97], v[104:105] op_sel_hi:[1,0]
	s_waitcnt lgkmcnt(2)
	v_pk_fma_f32 v[96:97], v[100:101], v[106:107], v[110:111]
	v_pk_fma_f32 v[98:99], v[102:103], v[108:109], v[112:113]
	s_waitcnt lgkmcnt(0)
	v_pk_fma_f32 v[100:101], v[124:125], v[118:119], v[114:115]
	v_pk_fma_f32 v[102:103], v[122:123], v[120:121], v[116:117]
	global_store_dwordx4 v[146:147], v[100:103], off
	global_store_dwordx4 v[146:147], v[96:99], off offset:16
	ds_read_b128 v[96:99], v251 offset:10256
	s_nop 0
	ds_read_b128 v[100:103], v251 offset:26640
	ds_read_b128 v[106:109], v251 offset:26624
	ds_read_b128 v[110:113], v251 offset:10240
	v_pk_mul_f32 v[114:115], v[90:91], v[104:105] op_sel_hi:[1,0]
	v_pk_mul_f32 v[116:117], v[88:89], v[104:105] op_sel_hi:[1,0]
	s_waitcnt lgkmcnt(2)
	v_pk_fma_f32 v[88:89], v[92:93], v[96:97], v[100:101]
	v_pk_fma_f32 v[90:91], v[94:95], v[98:99], v[102:103]
	s_waitcnt lgkmcnt(0)
	v_pk_fma_f32 v[92:93], v[116:117], v[110:111], v[106:107]
	v_pk_fma_f32 v[94:95], v[114:115], v[112:113], v[108:109]
	global_store_dwordx4 v[146:147], v[92:95], off offset:2048
	global_store_dwordx4 v[146:147], v[88:91], off offset:2064
	ds_read_b128 v[88:91], v251 offset:12304
	s_nop 0
	ds_read_b128 v[92:95], v251 offset:28688
	ds_read_b128 v[96:99], v251 offset:28672
	ds_read_b128 v[100:103], v251 offset:12288
	v_add_co_u32_e32 v106, vcc, s17, v0
	v_pk_mul_f32 v[108:109], v[82:83], v[104:105] op_sel_hi:[1,0]
	v_pk_mul_f32 v[110:111], v[80:81], v[104:105] op_sel_hi:[1,0]
	v_addc_co_u32_e32 v107, vcc, 0, v1, vcc
	s_waitcnt lgkmcnt(2)
	v_pk_fma_f32 v[80:81], v[84:85], v[88:89], v[92:93]
	v_pk_fma_f32 v[82:83], v[86:87], v[90:91], v[94:95]
	s_waitcnt lgkmcnt(0)
	v_pk_fma_f32 v[84:85], v[110:111], v[100:101], v[96:97]
	v_pk_fma_f32 v[86:87], v[108:109], v[102:103], v[98:99]
	global_store_dwordx4 v[106:107], v[84:87], off
	global_store_dwordx4 v[106:107], v[80:83], off offset:16
	ds_read_b128 v[80:83], v251 offset:14352
	s_nop 0
	ds_read_b128 v[84:87], v251 offset:30736
	ds_read_b128 v[88:91], v251 offset:30720
	ds_read_b128 v[92:95], v251 offset:14336
	v_pk_mul_f32 v[96:97], v[74:75], v[104:105] op_sel_hi:[1,0]
	v_pk_mul_f32 v[98:99], v[72:73], v[104:105] op_sel_hi:[1,0]
	s_waitcnt lgkmcnt(2)
	v_pk_fma_f32 v[72:73], v[76:77], v[80:81], v[84:85]
	v_pk_fma_f32 v[74:75], v[78:79], v[82:83], v[86:87]
	s_waitcnt lgkmcnt(0)
	v_pk_fma_f32 v[76:77], v[98:99], v[92:93], v[88:89]
	v_pk_fma_f32 v[78:79], v[96:97], v[94:95], v[90:91]
	global_store_dwordx4 v[106:107], v[76:79], off offset:2048
	global_store_dwordx4 v[106:107], v[72:75], off offset:2064
	s_branch .LBB0_2433
